# A2: no ALIGN_EPI barriers on non-final units in the ff1 and w_in unit loops (each half's epilogue overlaps the other half's MFMAs; the one-barrier stagger continues through the transition); on top of
# baseline (speedup 1.0000x reference)
.Ln1_sp4:
.Ln1_sp4_j:
	s_waitcnt lgkmcnt(0)
	s_barrier
	s_setprio 1
	s_waitcnt lgkmcnt(0)
	v_mfma_f32_16x16x32_bf16 v[60:63], v[140:143], v[176:179], v[60:63]
	v_mfma_f32_16x16x32_bf16 v[56:59], v[152:155], v[176:179], v[56:59]
	v_mfma_f32_16x16x32_bf16 v[44:47], v[140:143], v[188:191], v[44:47]
	v_mfma_f32_16x16x32_bf16 v[40:43], v[152:155], v[188:191], v[40:43]
	v_mfma_f32_16x16x32_bf16 v[28:31], v[140:143], v[196:199], v[28:31]
	v_mfma_f32_16x16x32_bf16 v[24:27], v[152:155], v[196:199], v[24:27]
	v_mfma_f32_16x16x32_bf16 v[12:15], v[140:143], v[204:207], v[12:15]
	v_mfma_f32_16x16x32_bf16 v[8:11], v[152:155], v[204:207], v[8:11]
	v_mfma_f32_16x16x32_bf16 v[60:63], v[148:151], v[180:183], v[60:63]
	v_mfma_f32_16x16x32_bf16 v[56:59], v[156:159], v[180:183], v[56:59]
	v_mfma_f32_16x16x32_bf16 v[44:47], v[148:151], v[192:195], v[44:47]
	v_mfma_f32_16x16x32_bf16 v[40:43], v[156:159], v[192:195], v[40:43]
	v_mfma_f32_16x16x32_bf16 v[28:31], v[148:151], v[200:203], v[28:31]
	v_mfma_f32_16x16x32_bf16 v[24:27], v[156:159], v[200:203], v[24:27]
	v_mfma_f32_16x16x32_bf16 v[12:15], v[148:151], v[208:211], v[12:15]
	v_mfma_f32_16x16x32_bf16 v[8:11], v[156:159], v[208:211], v[8:11]
	s_setprio 0
	s_setprio 1
	v_mfma_f32_16x16x32_bf16 v[52:55], v[160:163], v[176:179], v[52:55]
	v_mfma_f32_16x16x32_bf16 v[48:51], v[168:171], v[176:179], v[48:51]
	v_mfma_f32_16x16x32_bf16 v[36:39], v[160:163], v[188:191], v[36:39]
	v_mfma_f32_16x16x32_bf16 v[32:35], v[168:171], v[188:191], v[32:35]
	v_mfma_f32_16x16x32_bf16 v[20:23], v[160:163], v[196:199], v[20:23]
	v_mfma_f32_16x16x32_bf16 v[16:19], v[168:171], v[196:199], v[16:19]
	v_mfma_f32_16x16x32_bf16 v[4:7], v[160:163], v[204:207], v[4:7]
	v_mfma_f32_16x16x32_bf16 v[0:3], v[168:171], v[204:207], v[0:3]
	v_mfma_f32_16x16x32_bf16 v[52:55], v[164:167], v[180:183], v[52:55]
	v_mfma_f32_16x16x32_bf16 v[48:51], v[172:175], v[180:183], v[48:51]
	v_mfma_f32_16x16x32_bf16 v[36:39], v[164:167], v[192:195], v[36:39]
	v_mfma_f32_16x16x32_bf16 v[32:35], v[172:175], v[192:195], v[32:35]
	v_mfma_f32_16x16x32_bf16 v[20:23], v[164:167], v[200:203], v[20:23]
	v_mfma_f32_16x16x32_bf16 v[16:19], v[172:175], v[200:203], v[16:19]
	v_mfma_f32_16x16x32_bf16 v[4:7], v[164:167], v[208:211], v[4:7]
	v_mfma_f32_16x16x32_bf16 v[0:3], v[172:175], v[208:211], v[0:3]
	s_setprio 0
	s_barrier
	s_add_i32 s89, s89, 2
	s_add_u32 s87, s87, 0x100
	s_addc_u32 s88, s88, 0
	s_add_u32 s6, s6, 0x100
	s_addc_u32 s7, s7, 0
	s_cmp_gt_u32 s89, 13
	s_cbranch_scc0 .LBB0_234
	s_and_b64 vcc, exec, s[10:11]
	s_cbranch_vccz .LBB0_237
	s_cmp_lg_u64 s[36:37], 0
	s_cbranch_scc1 .LBB0_237
	s_barrier

.LBB0_270:
	s_andn2_b64 vcc, exec, s[0:1]
	s_cbranch_vccnz .LBB0_229
	s_nop 0
	s_branch .LBB0_229

.Lk0_half4:
	s_setprio 0
	s_barrier
	s_add_i32 s84, s84, 2
	s_add_u32 s82, s82, 0x100
	s_addc_u32 s83, s83, 0
	s_add_u32 s0, s0, 0x100
	s_addc_u32 s1, s1, 0
	s_cmp_gt_u32 s84, 13
	s_cbranch_scc0 .LBB0_477
	s_and_b64 vcc, exec, s[10:11]
	s_cbranch_vccz .LBB0_480
	s_cmp_lg_u64 s[36:37], 0
	s_cbranch_scc1 .LBB0_480
	s_barrier

.LBB0_513:
	s_andn2_b64 vcc, exec, s[4:5]
	s_cbranch_vccnz .LBB0_472
	s_nop 0
	s_branch .LBB0_472
